# v055 CL: wave 0 waits for the next problem's gate loads at their first use (loop top), not right after the image DMA
# baseline (speedup 1.0000x reference)
; #define LAUNDER(x) do {} while (0)
; #define LAUNDER(x) asm volatile("" : "+v"(x))
; DEV ClProb cl_decode(const Frame& F, int p, int odd, int nhh) {
;     ...
;     const bf16_t* P = (const bf16_t*)(F.ws + WS_P); const bf16_t* Q = (const bf16_t*)(F.ws + WS_QKV);
; DEV void phase_cl(const Frame& F0, int l) {
;     ...
;     for (int p = F.bid; p < nprob; p += F.G) {
;         int lz = F.lane; LAUNDER(lz); const int h = lz >> 5, l31 = lz & 31;
;     ...
;         float* CS = (float*)(F.ws + WS_CLS) + (size_t)p * 512;
;         if (F.wave == 0) {
;             const int i = F.lane;
;             float g = gq, be = bq;
;             if (kind == 1) { g = log1pf(-exp2f(-(5.0f + 2.0f * (float)(hh - 4) + (float)d))); be = 0.f; }
.LBB0_494:
	s_mul_hi_i32 s0, s52, 0x78787879
	s_ashr_i32 s14, s0, 6
	s_lshr_b32 s15, s0, 31
	s_add_i32 s14, s14, s15
	s_ashr_i32 s16, s14, 31
	s_abs_i32 s14, s14
	v_mul_hi_u32 v0, s14, v168
	v_mul_lo_u32 v0, v0, s72
	v_sub_u32_e32 v0, s14, v0
	v_subrev_u32_e32 v2, s72, v0
	v_cmp_le_u32_e32 vcc, s72, v0
	s_ashr_i32 s0, s0, 5
	s_add_i32 s0, s0, s15
	v_cndmask_b32_e32 v0, v0, v2, vcc
	v_subrev_u32_e32 v2, s72, v0
	v_cmp_le_u32_e32 vcc, s72, v0
	s_and_b32 s94, s0, 1
	s_mulk_i32 s0, 0x44
	v_cndmask_b32_e32 v0, v0, v2, vcc
	v_xor_b32_e32 v0, s16, v0
	v_subrev_u32_e32 v179, s16, v0
	v_cmp_lt_i32_e64 s[16:17], 3, v179
	s_ashr_i32 s53, s52, 31
	s_and_b64 s[18:19], s[58:59], s[16:17]
	s_sub_i32 s93, s52, s0
	s_lshl_b64 s[14:15], s[52:53], 11
	s_add_u32 s54, s69, s14
	v_cndmask_b32_e64 v0, 0, 1, s[26:27]
	v_mov_b32_e32 v42, v66
	s_addc_u32 s55, s70, s15
	v_cmp_ne_u32_e64 s[14:15], 1, v0
	s_andn2_b64 vcc, exec, s[26:27]
	v_cndmask_b32_e64 v180, 1.0, v208, s[18:19]
	s_cbranch_vccnz .LBB0_519
	s_andn2_b64 vcc, exec, s[18:19]
	s_waitcnt vmcnt(0)
	v_mov_b32_e32 v0, v161
	v_mov_b32_e32 v2, v160
	s_cbranch_vccnz .LBB0_497
	v_add_u32_e32 v0, -4, v179
	v_cvt_f32_u32_e32 v0, v0
	v_cvt_f32_ubyte0_e32 v2, s94
	s_mov_b32 s0, 0x42fc0000
	v_fmaak_f32 v0, 2.0, v0, 0x40a00000
	v_add_f32_e32 v0, v0, v2
	v_cmp_lt_f32_e32 vcc, s0, v0
	v_mov_b32_e32 v2, 0x42800000
	s_and_b64 s[18:19], vcc, exec
	v_cndmask_b32_e32 v2, 0, v2, vcc
	v_sub_f32_e32 v0, v2, v0
	v_exp_f32_e32 v2, v0
	s_cselect_b32 s0, 0xffffffc0, 0
	v_mov_b32_e32 v0, 0
	v_ldexp_f32 v43, v2, s0
	v_sub_f32_e32 v4, 1.0, v43
	v_add_f32_e32 v2, -1.0, v4
	v_sub_f32_e32 v3, v2, v4
	v_sub_f32_e64 v2, -v43, v2
	v_add_f32_e32 v3, 1.0, v3
	v_add_f32_e32 v5, v2, v3
	v_frexp_mant_f32_e32 v6, v4
	v_cvt_f64_f32_e32 v[2:3], v4
	s_mov_b32 s0, 0x3f2aaaab
	v_frexp_exp_i32_f64_e32 v2, v[2:3]
	v_cmp_gt_f32_e32 vcc, s0, v6
	s_mov_b32 s0, 0x3f317218
	s_nop 0
	v_subbrev_co_u32_e32 v10, vcc, 0, v2, vcc
	v_sub_u32_e32 v2, 0, v10
	v_ldexp_f32 v3, v4, v2
	v_add_f32_e32 v4, -1.0, v3
	v_add_f32_e32 v6, 1.0, v3
	v_ldexp_f32 v2, v5, v2
	v_add_f32_e32 v5, 1.0, v4
	v_add_f32_e32 v7, -1.0, v6
	v_sub_f32_e32 v5, v3, v5
	v_sub_f32_e32 v3, v3, v7
	v_add_f32_e32 v5, v2, v5
	v_add_f32_e32 v2, v2, v3
	v_add_f32_e32 v11, v6, v2
	v_rcp_f32_e32 v13, v11
	v_sub_f32_e32 v3, v11, v6
	v_sub_f32_e32 v12, v2, v3
	v_add_f32_e32 v3, v4, v5
	v_mul_f32_e32 v15, v3, v13
	v_sub_f32_e32 v2, v3, v4
	v_mul_f32_e32 v4, v11, v15
	v_fma_f32 v6, v15, v11, -v4
	v_fmac_f32_e32 v6, v15, v12
	v_sub_f32_e32 v14, v5, v2
	v_add_f32_e32 v2, v4, v6
	v_sub_f32_e32 v5, v3, v2
	v_pk_add_f32 v[8:9], v[2:3], v[4:5] neg_lo:[0,1] neg_hi:[0,1]
	v_mov_b32_e32 v7, v2
	v_pk_add_f32 v[2:3], v[8:9], v[6:7] neg_lo:[0,1] neg_hi:[0,1]
	v_cmp_nlt_f32_e32 vcc, 1.0, v43
	v_add_f32_e32 v3, v14, v3
	v_add_f32_e32 v2, v2, v3
	v_add_f32_e32 v3, v5, v2
	v_mul_f32_e32 v14, v13, v3
	v_mul_f32_e32 v4, v11, v14
	v_fma_f32 v6, v14, v11, -v4
	v_fmac_f32_e32 v6, v14, v12
	v_sub_f32_e32 v5, v5, v3
	v_add_f32_e32 v11, v2, v5
	v_add_f32_e32 v2, v4, v6
	v_sub_f32_e32 v5, v3, v2
	v_pk_add_f32 v[8:9], v[2:3], v[4:5] neg_lo:[0,1] neg_hi:[0,1]
	v_mov_b32_e32 v7, v2
	v_pk_add_f32 v[2:3], v[8:9], v[6:7] neg_lo:[0,1] neg_hi:[0,1]
	s_nop 0
	v_add_f32_e32 v3, v11, v3
	v_add_f32_e32 v2, v2, v3
	v_add_f32_e32 v3, v15, v14
	v_add_f32_e32 v2, v5, v2
	v_sub_f32_e32 v4, v3, v15
	v_mul_f32_e32 v2, v13, v2
	v_sub_f32_e32 v4, v14, v4
	v_add_f32_e32 v4, v4, v2
	v_add_f32_e32 v6, v3, v4
	v_mul_f32_e32 v7, v6, v6
	v_fmamk_f32 v2, v7, 0x3e9b6dac, v204
	v_fmaak_f32 v147, v7, v2, 0x3f2aaada
	v_cvt_f32_i32_e32 v2, v10
	v_sub_f32_e32 v3, v6, v3
	v_sub_f32_e32 v3, v4, v3
	v_ldexp_f32 v8, v3, 1
	v_mul_f32_e32 v3, v6, v7
	v_ldexp_f32 v5, v6, 1
	v_pk_mul_f32 v[6:7], v[2:3], v[146:147]
	s_nop 0
	v_fma_f32 v4, v2, s0, -v6
	v_fmac_f32_e32 v4, 0xb102e308, v2
	v_pk_add_f32 v[2:3], v[6:7], v[4:5]
	s_mov_b32 s0, 0x33800000
	v_sub_f32_e32 v5, v3, v5
	v_sub_f32_e32 v5, v7, v5
	v_add_f32_e32 v9, v8, v5
	v_mov_b32_e32 v8, v6
	v_pk_add_f32 v[6:7], v[2:3], v[6:7] neg_lo:[0,1] neg_hi:[0,1]
	v_pk_add_f32 v[10:11], v[2:3], v[8:9]
	v_mov_b32_e32 v5, v2
	v_mov_b32_e32 v7, v11
	v_pk_add_f32 v[12:13], v[4:5], v[6:7] neg_lo:[0,1] neg_hi:[0,1]
	v_pk_add_f32 v[4:5], v[4:5], v[6:7]
	v_mov_b32_e32 v16, v3
	v_pk_add_f32 v[6:7], v[4:5], v[2:3] op_sel:[1,0] op_sel_hi:[0,1] neg_lo:[0,1] neg_hi:[0,1]
	v_pk_add_f32 v[14:15], v[10:11], v[6:7] op_sel_hi:[1,0] neg_lo:[0,1] neg_hi:[0,1]
	v_mov_b32_e32 v10, v11
	v_mov_b32_e32 v11, v5
	v_mov_b32_e32 v17, v6
	v_pk_add_f32 v[6:7], v[10:11], v[16:17] neg_lo:[0,1] neg_hi:[0,1]
	v_mov_b32_e32 v8, v9
	v_mov_b32_e32 v9, v2
	v_pk_add_f32 v[2:3], v[8:9], v[6:7] neg_lo:[0,1] neg_hi:[0,1]
	v_mov_b32_e32 v14, v12
	v_pk_add_f32 v[6:7], v[14:15], v[2:3]
	v_mov_b32_e32 v13, v5
	v_pk_add_f32 v[8:9], v[6:7], v[6:7] op_sel:[0,1] op_sel_hi:[1,0]
	s_nop 0
	v_pk_add_f32 v[4:5], v[4:5], v[8:9] op_sel:[1,0] op_sel_hi:[0,1]
	v_mov_b32_e32 v7, v4
	v_pk_add_f32 v[10:11], v[6:7], v[12:13] neg_lo:[0,1] neg_hi:[0,1]
	v_mov_b32_e32 v3, v8
	v_sub_f32_e32 v5, v6, v10
	v_pk_add_f32 v[2:3], v[2:3], v[10:11] neg_lo:[0,1] neg_hi:[0,1]
	v_sub_f32_e32 v5, v12, v5
	v_add_f32_e32 v2, v2, v5
	v_add_f32_e32 v2, v2, v3
	v_add_f32_e32 v2, v4, v2
	v_mov_b32_e32 v3, 0x7fc00000
	v_cndmask_b32_e32 v2, v3, v2, vcc
	v_cmp_neq_f32_e32 vcc, 1.0, v43
	v_mov_b32_e32 v3, 0xff800000
	s_nop 0
	v_cndmask_b32_e32 v2, v3, v2, vcc
	v_cmp_gt_f32_e32 vcc, s0, v43
	s_nop 1
	v_cndmask_b32_e64 v2, v2, -v43, vcc

; DEV void phase_cl(const Frame& F0, int l) {
;     ...
;         if (p + F.G < nprob) { cl_dma(F, cl_decode(F, p + F.G, odd, nhh)); if (F.wave == 0) CL_GATES(p + F.G); }
.LBB0_715:
	s_andn2_b64 vcc, exec, s[14:15]
	s_cbranch_vccnz .LBB0_719
	s_cmp_lg_u32 s33, 0
	s_cbranch_scc1 .LBB0_720
	v_ashrrev_i32_e32 v5, 31, v4
	v_lshlrev_b64 v[4:5], 6, v[4:5]
	v_lshl_add_u64 v[4:5], s[22:23], 0, v[4:5]
	s_lshl_b32 s0, s96, 4
	v_ashrrev_i32_e32 v3, 31, v2
	v_lshl_add_u64 v[4:5], v[4:5], 0, s[0:1]
	v_lshl_add_u64 v[2:3], v[2:3], 2, v[4:5]
	global_load_dword v160, v[2:3], off
	global_load_dword v161, v[2:3], off offset:32
	s_branch .LBB0_720
